# v18 + mLSTM K tile via LDS-DMA (global_load_lds) instead of VGPR staging + 4 ds_write_b128 per wave per chunk
# speedup vs baseline: 1.0013x; 1.0004x over previous
; #define LAS __attribute__((address_space(3)))
; #define KDMA(Kptr, i) __builtin_amdgcn_global_load_lds((const unsigned*)((const char*)(Kptr) + (unsigned)(tofs + (i) * 8192)), (LAS unsigned*)(L + (unsigned)wid * 1024u + (i) * 8192), 16, 0, 0)
; template <int DK, bool ML>
; DI void mixer_item(const int tid_in, unsigned char* smem, int S, int nch, int seq, int head, int dir, int split,
;                    const bf16_t* Qg, const bf16_t* Kg, const bf16_t* KTg, const bf16_t* VTg, bf16_t* Hout, const float* gates, float lgv) {
;     ...
;     {
;         unsigned lo0 = lane * 16, to0 = tid * 16; asm volatile("" : "+v"(lo0), "+v"(to0));
;         MK_BASES(lo0, to0)
;         (void)a_ks; (void)a_vt; (void)a_cs; (void)a_ps; (void)a_psw; (void)a_csw; (void)a_tv; (void)a_sv; (void)a_hv;
;         for (int i = 0; i < 64 * DK * 2 / 16 / 512; ++i) *(LAS u32x4*)LDSB(a_cp, 81920 + i * 8192) = (u32x4){0u, 0u, 0u, 0u};
;         if (tid < 128) *(LAS float*)LDSB(a_th, 7 * 512) = 0.f;
;         if (ML) {
; #pragma unroll
;             for (int i = 0; i < 3; ++i) {
;                 const unsigned ones = (i == 0 && (lo0 & (31u * 16u)) == 0u) ? 0x3F803F80u : 0u;
;                 *(LAS u32x4*)LDSB(a_cp, 32768 + i * 8192) = (u32x4){ones, ones, ones, ones};
;             }
;         }
;     }
;     ...
;     {
;         unsigned lofs = lane * 16, tofs = tid * 16; asm volatile("" : "+v"(lofs), "+v"(tofs));
;         const bf16_t* Kf = Kg + blk0 * (size_t)(128 * DK);
;         if (ML) {
; #pragma unroll
;             for (int i = 0; i < NKP; ++i) kst[i] = LDG(u32x4, Kf, tofs + i * 8192);
;         } else {
; #pragma unroll
;             for (int i = 0; i < NKP; ++i) KDMA(Kf, i);
;         }
;         const bf16_t* Qf = Qg + blk0 * (size_t)(128 * DK);
; #pragma unroll
;         for (int ks = 0; ks < KS; ++ks) qf[ks] = LDG(bf16x8, Qf + tb * KS * 512, lofs + ks * 1024);
;         const bf16_t* VTf = VTg + blk0 * (size_t)(256 * 128) + split * (2 * 8 * 512);
; #pragma unroll
;         for (int i = 0; i < 2; ++i) vtr[i] = LDG(u32x4, VTf, tofs + i * 8192);
;         if (ML) {
;             const float* gp = gates + (((size_t)seq * nch + c0) * 2 + dir) * 4 * 384 + head * 384;
;             g_pml = gp[128 + last]; g_cbl = gp[256 + last];
;             if (tid < 128) { g_b = gp[tid]; g_pm = gp[128 + tid]; g_cb = gp[256 + tid]; }
;         }
;     }
.LBB0_296:
	s_ashr_i32 s0, s22, 31
	v_readlane_b32 s1, v255, 34
	s_xor_b32 s0, s0, s1
	s_abs_i32 s1, s22
	v_readlane_b32 s2, v255, 36
	s_mul_hi_u32 s2, s1, s2
	v_readlane_b32 s5, v255, 35
	s_mul_i32 s3, s2, s5
	s_sub_i32 s1, s1, s3
	s_add_i32 s3, s2, 1
	s_sub_i32 s4, s1, s5
	s_cmp_ge_u32 s1, s5
	s_cselect_b32 s2, s3, s2
	s_cselect_b32 s1, s4, s1
	s_add_i32 s3, s2, 1
	s_cmp_ge_u32 s1, s5
	s_cselect_b32 s1, s3, s2
	s_xor_b32 s1, s1, s0
	s_sub_i32 s0, s1, s0
	v_readlane_b32 s1, v255, 33
	s_mul_i32 s1, s0, s1
	s_sub_i32 s1, s22, s1
	s_and_b32 s66, s1, 3
	s_bfe_u32 s11, s1, 0x10002
	s_bfe_u32 s56, s1, 0x20003
	s_ashr_i32 s96, s1, 5
	s_and_b32 s1, 4, s1
	s_cmp_eq_u32 s11, 0
	s_cselect_b64 s[36:37], -1, 0
	s_cmp_lg_u32 s1, 0
	s_cselect_b64 s[78:79], -1, 0
	s_cmp_lg_u32 s0, 0
	s_cbranch_scc0 .LBB0_356
	v_mov_b32_e32 v0, v234
	s_mov_b32 s44, s67
	v_lshlrev_b32_e32 v198, 4, v0
	v_and_b32_e32 v199, 0x3f0, v198
	v_mov_b32_e32 v3, v199
	v_mov_b32_e32 v4, v198
	s_mov_b32 s45, s67
	s_mov_b32 s46, s67
	v_add_u32_e32 v2, 0, v4
	s_mov_b32 s47, s67
	v_mov_b64_e32 v[6:7], s[44:45]
	s_movk_i32 s0, 0x7f
	v_add_u32_e32 v5, 0x14000, v2
	v_mov_b64_e32 v[8:9], s[46:47]
	v_cmp_lt_i32_e32 vcc, s0, v0
	s_movk_i32 s0, 0x80
	v_readfirstlane_b32 s2, v0
	ds_write_b128 v5, v[6:9]
	v_add_u32_e32 v5, 0x16000, v2
	v_cmp_gt_i32_e64 s[38:39], s0, v0
	ds_write_b128 v5, v[6:9]
	s_and_saveexec_b64 s[0:1], s[38:39]
	v_lshrrev_b32_e32 v4, 2, v4
	v_add_u32_e32 v4, 0, v4
	v_add_u32_e32 v4, 0x24e00, v4
	ds_write_b32 v4, v1
	s_or_b64 exec, exec, s[0:1]
	s_ashr_i32 s0, s2, 6
	s_cmpk_gt_u32 s2, 0xff
	s_cselect_b64 s[98:99], -1, 0
	s_sub_i32 s1, 7, s0
	v_and_b32_e32 v3, 0x1f0, v3
	s_cmpk_lt_u32 s2, 0x100
	v_cmp_eq_u32_e64 s[40:41], 0, v3
	v_mov_b32_e32 v3, 0x3f803f80
	s_cselect_b32 s42, s0, s1
	v_cndmask_b32_e64 v4, 0, v3, s[40:41]
	s_and_b64 s[0:1], s[36:37], exec
	v_mov_b32_e32 v5, v4
	v_mov_b32_e32 v6, v4
	v_mov_b32_e32 v7, v4
	v_readlane_b32 s0, v255, 29
	ds_write_b128 v2, v[4:7] offset:32768
	v_mov_b64_e32 v[4:5], s[44:45]
	s_cselect_b32 s0, 0, s0
	s_ashr_i32 s97, s96, 31
	v_readlane_b32 s1, v255, 31
	v_mov_b64_e32 v[6:7], s[46:47]
	s_lshl_b64 s[44:45], s[96:97], s1
	s_add_u32 s6, s44, s0
	s_addc_u32 s7, s45, 0
	s_lshl_b64 s[4:5], s[6:7], 2
	s_or_b32 s4, s4, s66
	s_lshl_b64 s[0:1], s[4:5], 15
	v_readlane_b32 s3, v255, 16
	ds_write_b128 v2, v[4:7] offset:40960
	ds_write_b128 v2, v[4:7] offset:49152
	v_mov_b32_e32 v2, v199
	v_mov_b32_e32 v3, v198
	s_add_u32 s8, s3, s0
	v_readlane_b32 s3, v255, 17
	s_addc_u32 s9, s3, s1
	v_readfirstlane_b32 s3, v3
	v_add_u32_e32 v5, 0x4000, v3
	v_add_u32_e32 v4, 0x2000, v3
	s_mov_b32 m0, s3
	s_nop 0
	global_load_lds_dwordx4 v3, s[8:9]
	s_add_i32 m0, m0, 0x2000
	s_nop 0
	global_load_lds_dwordx4 v4, s[8:9]
	s_add_i32 m0, m0, 0x2000
	s_nop 0
	global_load_lds_dwordx4 v5, s[8:9]
	v_add_u32_e32 v5, 0x6000, v3
	s_add_i32 m0, m0, 0x2000
	s_nop 0
	global_load_lds_dwordx4 v5, s[8:9]
	s_add_u32 s3, s94, s0
	s_addc_u32 s9, s95, s1
	s_lshl_b32 s0, s42, 12
	s_ashr_i32 s1, s0, 31
	s_lshl_b64 s[0:1], s[0:1], 1
	s_add_u32 s8, s3, s0
	s_addc_u32 s9, s9, s1
	v_add_u32_e32 v5, 0x400, v2
	global_load_dwordx4 v[106:109], v2, s[8:9]
	global_load_dwordx4 v[114:117], v5, s[8:9]
	v_add_u32_e32 v5, 0x800, v2
	s_lshl_b64 s[4:5], s[4:5], 16
	v_readlane_b32 s3, v255, 1
	global_load_dwordx4 v[118:121], v5, s[8:9]
	v_add_u32_e32 v5, 0xc00, v2
	s_add_u32 s3, s3, s4
	v_readlane_b32 s4, v255, 2
	global_load_dwordx4 v[126:129], v5, s[8:9]
	v_add_u32_e32 v5, 0x1000, v2
	s_addc_u32 s5, s4, s5
	s_lshl_b32 s4, s56, 14
	global_load_dwordx4 v[130:133], v5, s[8:9]
	v_add_u32_e32 v5, 0x1400, v2
	s_add_u32 s4, s3, s4
	global_load_dwordx4 v[134:137], v5, s[8:9]
	v_add_u32_e32 v5, 0x1800, v2
	v_add_u32_e32 v2, 0x1c00, v2
	s_addc_u32 s5, s5, 0
	global_load_dwordx4 v[138:141], v5, s[8:9]
	global_load_dwordx4 v[142:145], v2, s[8:9]
	global_load_dwordx4 v[146:149], v3, s[4:5]
	global_load_dwordx4 v[150:153], v4, s[4:5]
	s_and_b64 s[4:5], s[36:37], exec
	s_cselect_b32 s5, 0x7f, 0
	s_lshl_b64 s[6:7], s[6:7], 3
	s_lshl_b32 s4, s11, 2
	s_or_b32 s3, s6, s4
	s_mul_i32 s6, s7, 0x600
	s_mul_hi_u32 s7, s3, 0x600
	s_add_i32 s7, s7, s6
	s_mulk_i32 s3, 0x600
	v_readlane_b32 s8, v253, 46
	v_readlane_b32 s9, v253, 47
	s_add_u32 s6, s8, s3
	s_mul_i32 s3, s66, 0x180
	s_addc_u32 s7, s9, s7
	s_lshl_b32 s3, s3, 2
	s_add_u32 s6, s6, s3
	s_addc_u32 s7, s7, 0
	s_lshl_b32 s5, s5, 2
	v_mov_b32_e32 v2, s5
	global_load_dword v206, v2, s[6:7] offset:512
	global_load_dword v205, v2, s[6:7] offset:1024
	s_and_saveexec_b64 s[8:9], vcc
	s_xor_b64 s[16:17], exec, s[8:9]
	v_mov_b64_e32 v[194:195], v[0:1]
	v_writelane_b32 v255, s11, 39
	s_or_saveexec_b64 s[16:17], s[16:17]
	s_lshl_b32 s8, s56, 13
	v_mov_b32_e32 v209, 0
	v_mov_b32_e32 v204, 0
	v_mov_b32_e32 v200, 0
	v_mov_b32_e32 v201, 0
	s_xor_b64 exec, exec, s[16:17]
	s_cbranch_execz .LBB0_303
	v_ashrrev_i32_e32 v195, 31, v0
	v_mov_b32_e32 v194, v0
	v_lshl_add_u64 v[2:3], v[194:195], 2, s[6:7]
	global_load_dword v201, v[2:3], off
	global_load_dword v200, v[2:3], off offset:512
	global_load_dword v204, v[2:3], off offset:1024

; #define LAS __attribute__((address_space(3)))
; template <int DK, bool ML>
; DI void mixer_item(const int tid_in, unsigned char* smem, int S, int nch, int seq, int head, int dir, int split,
;                    const bf16_t* Qg, const bf16_t* Kg, const bf16_t* KTg, const bf16_t* VTg, bf16_t* Hout, const float* gates, float lgv) {
;     ...
;         if (ML) {
; #pragma unroll
;             for (int i = 0; i < NKP; ++i) *(LAS u32x4*)LDSB(a_cp, i * 8192) = kst[i];
;         }
; #pragma unroll
;         for (int i = 0; i < 2; ++i) *(LAS u32x4*)LDSB(a_cp, 65536 + i * 8192) = vtr[i];
;         float dec, m_new = 0.f;
;         if (ML) {
;             const float Ml = fmaxf(m, g_pml);
;             dec = __expf(m - Ml); m_new = g_cbl + Ml;
;             if (tid < 128) {
;                 const float M = fmaxf(m, g_pm);
;                 *(LAS float*)LDSB(a_th, 0) = g_b * 1.44269504089f; *(LAS float*)LDSB(a_th, 512) = M * 1.44269504089f; *(LAS float*)LDSB(a_th, 1024) = __expf(m - M);
;                 *(LAS float*)LDSB(a_th, 1536) = __expf(-g_cb - M); *(LAS float*)LDSB(a_th, 2048) = __expf(g_b - Ml); *(LAS float*)LDSB(a_th, 2560) = 0.f;
;             }
;         } else {
;             dec = __expf(lgv * 128.f);
;             if (ci == 0 && tid < 128) { *(LAS float*)LDSB(a_th, 1024) = __expf(lgv * (float)(dir ? (128 - tid) : (tid + 1))); *(LAS float*)LDSB(a_th, 2048) = __expf(lgv * (float)(dir ? tid : (127 - tid))); }
;         }
;         auto do_d0 = [&]() {
; #pragma unroll
;         for (int i = 0; i < 2; ++i) {
;             const unsigned pidx = (unsigned)i * 512u + (tofs >> 4);
;             const unsigned s0 = ((pidx >> 6) & 7u) * 16u + ((pidx >> 5) & 1u) * 8u;
;             const u32x4 vv = *(const LAS u32x4*)LDSB(a_cp, 65536 + i * 8192);
;             const f32x4 w0 = *(const LAS f32x4*)(L + 147456u + 4u * 512u + s0 * 4u), w1 = *(const LAS f32x4*)(L + 147456u + 4u * 512u + s0 * 4u + 16u);
;             u32x4 o;
;             o.x = pk2(bflo(vv.x) * w0[0], bfhi(vv.x) * w0[1]); o.y = pk2(bflo(vv.y) * w0[2], bfhi(vv.y) * w0[3]);
;             o.z = pk2(bflo(vv.z) * w1[0], bfhi(vv.z) * w1[1]); o.w = pk2(bflo(vv.w) * w1[2], bfhi(vv.w) * w1[3]);
;             *(LAS u32x4*)LDSB(a_cp, VTW_OFF + i * 8192) = o;
;         }
;         if (ML && tid < 16) {
;             const unsigned s0 = (unsigned)(tid >> 1) * 16u + (unsigned)(tid & 1) * 8u;
.LBB0_305:
	v_mov_b32_e32 v197, v199
	v_mov_b32_e32 v0, v198
	v_mov_b32_e32 v2, v1
	v_max_f32_e32 v6, v206, v206
	v_add_u32_e32 v2, 0, v0
	v_max_f32_e32 v5, v209, v209
	v_add_u32_e32 v4, 0x10000, v2
	v_add_u32_e32 v3, 0x12000, v2
	v_max_f32_e32 v210, v5, v6
	ds_write_b128 v4, v[146:149]
	ds_write_b128 v3, v[150:153]
	s_and_saveexec_b64 s[42:43], s[38:39]
	s_cbranch_execz .LBB0_307
	v_lshrrev_b32_e32 v6, 2, v0
	v_max_f32_e32 v7, v200, v200
	v_add_u32_e32 v6, 0, v6
	v_max_f32_e32 v5, v5, v7
	v_mul_f32_e32 v7, 0x3fb8aa3b, v201
	v_add_u32_e32 v8, 0x24000, v6
	ds_write_b32 v8, v7
	v_mul_f32_e32 v7, 0x3fb8aa3b, v5
	v_add_u32_e32 v8, 0x24200, v6
	ds_write_b32 v8, v7
	v_sub_f32_e32 v7, v209, v5
	v_mul_f32_e32 v7, 0x3fb8aa3b, v7
	v_sub_f32_e64 v5, -v204, v5
	v_exp_f32_e32 v7, v7
	v_mul_f32_e32 v5, 0x3fb8aa3b, v5
	v_exp_f32_e32 v5, v5
	v_add_u32_e32 v8, 0x24400, v6
	ds_write_b32 v8, v7
	v_add_u32_e32 v7, 0x24600, v6
	ds_write_b32 v7, v5
	v_sub_f32_e32 v5, v201, v210
	v_mul_f32_e32 v5, 0x3fb8aa3b, v5
	v_exp_f32_e32 v5, v5
	v_add_u32_e32 v7, 0x24800, v6
	ds_write_b32 v7, v5
	v_add_u32_e32 v5, 0x24a00, v6
	ds_write_b32 v5, v1
.LBB0_307:
	s_or_b64 exec, exec, s[42:43]
	v_lshrrev_b32_e32 v8, 4, v0
	s_waitcnt vmcnt(0) lgkmcnt(0)
	s_barrier
	v_and_b32_e32 v8, 0x1e0, v8
	ds_read_b128 v[4:7], v4
	v_add_u32_e32 v8, 0, v8
	v_add_u32_e32 v50, 0x24800, v8
	ds_read_b128 v[8:11], v50
	ds_read_b128 v[12:15], v50 offset:16
	s_waitcnt lgkmcnt(0)
	v_lshlrev_b32_e32 v48, 16, v4
	v_and_b32_e32 v49, 0xffff0000, v4
	v_pk_mul_f32 v[8:9], v[8:9], v[48:49]
	s_nop 0
	v_cvt_pk_bf16_f32 v4, v8, v9
	v_lshlrev_b32_e32 v8, 16, v5
	v_and_b32_e32 v9, 0xffff0000, v5
	v_pk_mul_f32 v[8:9], v[10:11], v[8:9]
	s_nop 0
	v_cvt_pk_bf16_f32 v5, v8, v9
	v_lshlrev_b32_e32 v8, 16, v6
	v_and_b32_e32 v9, 0xffff0000, v6
	v_pk_mul_f32 v[8:9], v[12:13], v[8:9]
	s_nop 0
	v_cvt_pk_bf16_f32 v6, v8, v9
	v_lshlrev_b32_e32 v8, 16, v7
	v_and_b32_e32 v9, 0xffff0000, v7
	v_pk_mul_f32 v[8:9], v[14:15], v[8:9]
	s_nop 0
	v_cvt_pk_bf16_f32 v7, v8, v9
	v_add_u32_e32 v8, 0x18000, v2
	ds_write_b128 v8, v[4:7]
	ds_read_b128 v[4:7], v3
	ds_read_b128 v[8:11], v50
	ds_read_b128 v[12:15], v50 offset:16
	v_add_u32_e32 v2, 0x1a000, v2
	s_waitcnt lgkmcnt(2)
	v_lshlrev_b32_e32 v48, 16, v4
	v_and_b32_e32 v49, 0xffff0000, v4
	s_waitcnt lgkmcnt(1)
	v_pk_mul_f32 v[8:9], v[8:9], v[48:49]
	s_nop 0
	v_cvt_pk_bf16_f32 v4, v8, v9
	v_lshlrev_b32_e32 v8, 16, v5
	v_and_b32_e32 v9, 0xffff0000, v5
	v_pk_mul_f32 v[8:9], v[10:11], v[8:9]
	s_nop 0
	v_cvt_pk_bf16_f32 v5, v8, v9
	v_lshlrev_b32_e32 v8, 16, v6
	v_and_b32_e32 v9, 0xffff0000, v6
	s_waitcnt lgkmcnt(0)
	v_pk_mul_f32 v[8:9], v[12:13], v[8:9]
	s_nop 0
	v_cvt_pk_bf16_f32 v6, v8, v9
	v_lshlrev_b32_e32 v8, 16, v7
	v_and_b32_e32 v9, 0xffff0000, v7
	v_pk_mul_f32 v[8:9], v[14:15], v[8:9]
	s_nop 0
	v_cvt_pk_bf16_f32 v7, v8, v9
	ds_write_b128 v2, v[4:7]
	s_and_saveexec_b64 s[42:43], s[40:41]
	s_cbranch_execz .LBB0_309
	ds_read_b128 v[2:5], v207
	ds_read_b128 v[6:9], v207 offset:16
	s_waitcnt lgkmcnt(1)
	v_cvt_pk_bf16_f32 v2, v2, v3
	v_cvt_pk_bf16_f32 v3, v4, v5
	s_waitcnt lgkmcnt(0)
	v_cvt_pk_bf16_f32 v4, v6, v7
	v_cvt_pk_bf16_f32 v5, v8, v9
	ds_write_b128 v208, v[2:5] offset:40960

; #define BAR_LDS() do { asm volatile("s_waitcnt lgkmcnt(0)" ::: "memory"); __builtin_amdgcn_s_barrier(); asm volatile("" ::: "memory"); } while (0)
; template <int DK, bool ML>
; DI void mixer_item(const int tid_in, unsigned char* smem, int S, int nch, int seq, int head, int dir, int split,
;                    const bf16_t* Qg, const bf16_t* Kg, const bf16_t* KTg, const bf16_t* VTg, bf16_t* Hout, const float* gates, float lgv) {
;     ...
;         BAR_LDS();
;         if (has_next) {
;             if (ML) {
; #pragma unroll
;                 for (int i = 0; i < NKP; ++i) kst[i] = LDG(u32x4, Kfn, tofs + i * 8192);
;                 const bf16_t* Qfn = Qg + blkn * (size_t)(128 * DK);
; #pragma unroll
;                 for (int ks = 0; ks < KS; ++ks) qfn[ks] = LDG(bf16x8, Qfn + tb * KS * 512, lofs + ks * 1024);
;                 const bf16_t* VTfn = VTg + blkn * (size_t)(256 * 128) + split * (2 * 8 * 512);
; #pragma unroll
;                 for (int i = 0; i < 2; ++i) vtr[i] = LDG(u32x4, VTfn, tofs + i * 8192);
;                 const float* gp = gates + (((size_t)seq * nch + cn) * 2 + dir) * 4 * 384 + head * 384;
;                 g_pml = gp[128 + last]; g_cbl = gp[256 + last];
;                 if (tid < 128) { g_b = gp[tid]; g_pm = gp[128 + tid]; g_cb = gp[256 + tid]; }
.LBB0_321:
	s_add_i32 s58, s83, -1
	s_and_b64 s[54:55], s[36:37], exec
	s_cselect_b32 s58, s58, s87
	s_cmp_lt_u32 s83, s23
	s_waitcnt lgkmcnt(0)
	s_barrier
	s_cselect_b64 s[54:55], -1, 0
	s_and_b64 vcc, exec, s[54:55]
	v_add_u32_e32 v190, 0x400, v197
	v_add_u32_e32 v191, 0x800, v197
	v_add_u32_e32 v192, 0xc00, v197
	v_add_u32_e32 v193, 0x1000, v197
	v_add_u32_e32 v189, 0x1400, v197
	v_add_u32_e32 v187, 0x1800, v197
	v_add_u32_e32 v188, 0x1c00, v197
	s_cbranch_vccz .LBB0_326
	v_readfirstlane_b32 s62, v0
	s_add_i32 s59, s58, s2
	s_mov_b32 m0, s62
	s_and_b64 s[60:61], exec, s[54:55]
	s_cselect_b32 s60, s59, s58
	s_ashr_i32 s61, s60, 31
	s_add_u32 s60, s44, s60
	s_addc_u32 s61, s45, s61
	s_lshl_b64 s[60:61], s[60:61], 2
	s_or_b64 s[60:61], s[60:61], s[84:85]
	s_lshl_b64 s[62:63], s[60:61], 15
	v_readlane_b32 vcc_lo, v255, 16
	s_add_u32 vcc_lo, vcc_lo, s62
	v_readlane_b32 vcc_hi, v255, 17
	s_addc_u32 vcc_hi, vcc_hi, s63
	s_add_u32 s62, s26, s62
	s_addc_u32 s63, s27, s63
	s_lshl_b64 s[60:61], s[60:61], 16
	v_add_u32_e32 v3, 0x4000, v0
	s_add_u32 s60, s86, s60
	s_addc_u32 s61, s12, s61
	s_waitcnt lgkmcnt(0)
	v_add_u32_e32 v2, 0x2000, v0
	s_nop 1
	global_load_lds_dwordx4 v0, vcc
	s_add_i32 m0, m0, 0x2000
	s_nop 0
	global_load_lds_dwordx4 v2, vcc
	s_add_i32 m0, m0, 0x2000
	s_nop 0
	global_load_lds_dwordx4 v3, vcc
	v_add_u32_e32 v3, 0x6000, v0
	s_add_i32 m0, m0, 0x2000
	s_nop 0
	global_load_lds_dwordx4 v3, vcc
	global_load_dwordx4 v[154:157], v197, s[62:63]
	global_load_dwordx4 v[158:161], v190, s[62:63]
	global_load_dwordx4 v[162:165], v191, s[62:63]
	global_load_dwordx4 v[166:169], v192, s[62:63]
	global_load_dwordx4 v[170:173], v193, s[62:63]
	global_load_dwordx4 v[174:177], v189, s[62:63]
	global_load_dwordx4 v[178:181], v187, s[62:63]
	global_load_dwordx4 v[182:185], v188, s[62:63]
	global_load_dwordx4 v[146:149], v0, s[60:61]
	global_load_dwordx4 v[150:153], v2, s[60:61]
	s_ashr_i32 s61, s59, 31
	s_add_u32 s60, s44, s59
	s_addc_u32 s61, s45, s61
	s_lshl_b64 s[60:61], s[60:61], 3
	s_or_b32 s59, s60, s4
	s_mul_i32 s60, s61, 0x600
	s_mul_hi_u32 s61, s59, 0x600
	s_add_i32 s61, s61, s60
	s_mulk_i32 s59, 0x600
	s_add_u32 s60, s34, s59
	s_addc_u32 s61, s35, s61
	v_mov_b32_e32 v0, s5
	global_load_dword v206, v0, s[60:61] offset:512
	global_load_dword v213, v0, s[60:61] offset:1024
	s_and_saveexec_b64 s[62:63], s[38:39]
	s_cbranch_execz .LBB0_324
	v_lshl_add_u64 v[2:3], v[194:195], 2, s[60:61]
	global_load_dword v201, v[2:3], off
	global_load_dword v200, v[2:3], off offset:512
	global_load_dword v204, v[2:3], off offset:1024
